# ring loader: NA loop issues the K and V tiles of a step in one straight-line pass; DILP/MEM loop loaders use a direct compare chain instead of the flag-pair switch
# baseline (speedup 1.0000x reference)
.LBB0_358:
	s_mov_b32 s21, 1
	s_and_b64 vcc, exec, s[80:81]
	s_cbranch_vccnz .LBB0_391
	s_cmp_lt_i32 s69, 2
	s_cbranch_scc1 .Ldl_m01
	s_cmp_eq_u32 s69, 2
	s_cbranch_scc0 .Ldl_m3
	s_lshl_b32 s0, s71, 5
	s_and_b32 s0, s0, 0x60
	s_mul_i32 s1, s27, s0
	s_mul_hi_u32 s21, s26, s0
	s_add_i32 s21, s21, s1
	s_mul_i32 s0, s26, s0
	s_add_u32 s0, s12, s0
	s_addc_u32 s1, s13, s21
	s_ashr_i32 s21, s71, 2
	s_mul_hi_i32 vcc_lo, s21, 0x3800
	s_mulk_i32 s21, 0x3800
	s_add_u32 s0, s0, s21
	s_addc_u32 s1, s1, vcc_lo

.Ldl_cnt:
	s_add_i32 s0, s65, 1
	s_cmp_lg_u32 s0, 6
	s_cselect_b32 s65, s0, 0
	s_add_i32 s71, s71, 1
	s_cmp_lg_u32 s71, s53
	s_mov_b32 s21, 0
	s_cbranch_scc1 .LBB0_391
	s_branch .Ldl_trans
.Ldl_m01:
	s_cmp_eq_u32 s69, 0
	s_cbranch_scc1 .Ldl_m0
	s_lshl_b32 s0, s71, 5
	s_add_i32 s0, s67, s0
	s_sub_i32 s0, s0, 64
	s_max_i32 s0, s0, 0
	s_sub_i32 s1, s50, 32
	s_min_i32 s0, s0, s1
	s_mul_i32 s1, s27, s0
	s_mul_hi_u32 s16, s26, s0
	s_add_i32 s16, s16, s1
	s_mul_i32 s0, s26, s0
	s_add_u32 s0, s12, s0
	s_addc_u32 s1, s13, s16
	s_branch .Ldl_dma
.Ldl_m0:
	s_ashr_i32 s0, s71, 31
	s_mul_hi_u32 s1, s26, s71
	s_mul_i32 s0, s26, s0
	s_add_i32 s0, s1, s0
	s_mul_i32 s1, s27, s71
	s_add_i32 s1, s0, s1
	s_mul_i32 s0, s26, s71
	s_lshl_b64 s[0:1], s[0:1], 5
	s_add_u32 s0, s12, s0
	s_addc_u32 s1, s13, s1
	s_branch .Ldl_dma
.Ldl_m3:
	s_ashr_i32 s0, s71, 1
	s_mul_hi_i32 s1, s0, 0xe0000
	s_mul_i32 s0, s0, 0xe0000
	s_add_u32 s0, s12, s0
	s_addc_u32 s1, s13, s1
	s_bfe_i32 s16, s71, 0x10000
	s_and_b32 s16, s16, s98
	s_add_u32 s0, s0, s16
	s_addc_u32 s1, s1, 0
	s_lshl_b32 s16, s65, 14
	s_add_i32 s16, s30, s16
	s_mov_b32 m0, s16
	s_nop 0
	global_load_lds_dwordx4 v94, s[0:1]
	s_add_i32 m0, s16, 0x400
	s_nop 0
	global_load_lds_dwordx4 v183, s[0:1]
	s_branch .Ldl_cnt
.Ldl_trans:
	s_add_i32 s0, s63, s82
	s_add_i32 s19, s19, s42
	s_add_i32 s1, s0, -3
	s_cmp_gt_i32 s0, 2
	s_cselect_b32 s0, s1, s0
	s_cmp_eq_u32 s0, 1
	s_cselect_b32 s1, s83, 0x600
	s_cmp_lg_u32 s0, 0
	s_cselect_b32 s16, s1, 0x300
	s_cmp_gt_i32 s63, 1
	s_cselect_b64 s[0:1], -1, 0
	s_cmp_ge_i32 s19, s16
	s_cselect_b64 s[16:17], -1, 0
	s_and_b64 s[28:29], s[16:17], exec
	s_cselect_b32 s19, s66, s19
	s_and_b64 s[0:1], s[16:17], s[0:1]
	s_cmp_lg_u64 s[16:17], 0
	s_addc_u32 s63, s63, 0
	s_mov_b32 s21, 1
	s_and_b64 vcc, exec, s[0:1]
	s_cbranch_vccnz .LBB0_390
	s_add_i32 s0, s63, s82
	s_add_i32 s1, s0, -3
	s_cmp_gt_i32 s0, 2
	s_cselect_b32 s0, s1, s0
	s_cmp_eq_u32 s0, 1
	s_cselect_b32 s1, 1, 2
	s_cmp_lg_u32 s0, 0
	s_cselect_b32 s0, s1, 0
	s_cmp_lt_i32 s0, 1
	s_cbranch_scc1 .LBB0_387
	s_cmp_lg_u32 s0, 1
	s_mov_b64 s[0:1], -1
	s_cbranch_scc0 .LBB0_384
	s_mul_hi_i32 s0, s19, 0x2aaaaaab
	s_lshr_b32 s1, s0, 31
	s_ashr_i32 s0, s0, 7
	s_add_i32 s0, s0, s1
	s_add_i32 s53, s0, 1
	s_mulk_i32 s0, 0x300
	s_sub_i32 s0, s19, s0
	s_mul_i32 s1, s0, 0x2aab
	s_lshr_b32 s12, s1, 31
	s_ashr_i32 s1, s1, 19
	s_add_i32 s1, s1, s12
	s_mul_i32 s12, s1, 48
	s_sub_i32 s0, s0, s12
	s_sext_i32_i16 s69, s0
	s_and_b32 s28, s69, 7
	s_mul_hi_i32 s0, s1, 0x1c00000
	s_mul_i32 s1, s1, 0x1c00000
	s_add_u32 s12, s96, s1
	s_addc_u32 s13, s97, s0
	s_lshl_b32 s0, s69, 4
	s_and_b32 s0, s0, 0xffffff80
	s_add_i32 s98, s0, 0xf00
	s_lshl_b64 s[0:1], s[98:99], 1
	s_add_u32 s29, s12, s0
	s_addc_u32 s71, s13, s1
	s_cmp_lg_u32 s53, 2
	s_mov_b64 s[0:1], -1
	s_cbranch_scc0 .LBB0_381
	s_cmp_eq_u32 s53, 0
	s_cselect_b64 s[0:1], -1, 0
	s_add_i32 s12, s19, 0x2ff
	s_lshr_b32 s13, s28, 1
	s_and_b32 s16, s69, 1
	s_cmpk_lt_u32 s12, 0x5ff
	s_mulk_i32 s13, 0x3800
	s_cselect_b32 s12, s13, 0
	s_cselect_b32 s13, s16, s28
	s_lshl_b32 s16, s13, 8
	s_and_b64 s[0:1], s[0:1], exec
	s_movk_i32 s0, 0x800
	s_cselect_b32 s17, s0, 0x200
	s_mov_b32 s0, 0xe000
	s_cselect_b32 s98, 0x3800, s0
	s_add_u32 s12, s29, s12
	s_addc_u32 s13, s71, 0
	s_mov_b64 s[0:1], 0
	s_mov_b32 s21, s98
	s_mov_b64 s[26:27], s[98:99]

.LBB0_443:
	s_cmp_lt_i32 s69, 2
	s_cbranch_scc1 .Lml_m01
	s_cmp_eq_u32 s69, 2
	s_cbranch_scc0 .Lml_m3
	s_lshl_b32 s16, s71, 5
	s_and_b32 s16, s16, 0x60
	s_mul_i32 s17, s27, s16
	s_mul_hi_u32 s20, s26, s16
	s_add_i32 s20, s20, s17
	s_mul_i32 s16, s26, s16
	s_add_u32 s16, s12, s16
	s_addc_u32 s17, s13, s20
	s_ashr_i32 s20, s71, 2
	s_mul_hi_i32 s21, s20, 0x3800
	s_mulk_i32 s20, 0x3800
	s_add_u32 s20, s16, s20
	s_addc_u32 s21, s17, s21

.Lml_m01:
	s_cmp_eq_u32 s69, 0
	s_cbranch_scc1 .Lml_m0
	s_lshl_b32 s0, s71, 5
	s_add_i32 s0, s67, s0
	s_sub_i32 s0, s0, 64
	s_max_i32 s0, s0, 0
	s_sub_i32 s1, s50, 32
	s_min_i32 s0, s0, s1
	s_mul_i32 s1, s27, s0
	s_mul_hi_u32 s14, s26, s0
	s_add_i32 s14, s14, s1
	s_mul_i32 s0, s26, s0
	s_add_u32 s20, s12, s0
	s_addc_u32 s21, s13, s14
	s_branch .Lml_dma
.Lml_m0:
	s_ashr_i32 s0, s71, 31
	s_mul_hi_u32 s1, s26, s71
	s_mul_i32 s0, s26, s0
	s_add_i32 s0, s1, s0
	s_mul_i32 s1, s27, s71
	s_add_i32 s1, s0, s1
	s_mul_i32 s0, s26, s71
	s_lshl_b64 s[0:1], s[0:1], 5
	s_add_u32 s20, s12, s0
	s_addc_u32 s21, s13, s1
	s_branch .Lml_dma
.Lml_m3:
	s_ashr_i32 s0, s71, 1
	s_mul_hi_i32 s1, s0, 0xe0000
	s_mul_i32 s0, s0, 0xe0000
	s_add_u32 s0, s12, s0
	s_addc_u32 s1, s13, s1
	s_bfe_i32 s14, s71, 0x10000
	s_and_b32 s14, s14, s98
	s_add_u32 s0, s0, s14
	s_addc_u32 s1, s1, 0
	s_lshl_b32 s14, s65, 14
	s_add_i32 s14, s30, s14
	s_mov_b32 m0, s14
	s_nop 0
	global_load_lds_dwordx4 v94, s[0:1]
	s_add_i32 m0, s14, 0x400
	s_nop 0
	global_load_lds_dwordx4 v183, s[0:1]
	s_branch .Lml_cnt
.Lml_trans:
	s_add_i32 s0, s63, s82
	s_add_i32 s19, s19, s42
	s_add_i32 s1, s0, -3
	s_cmp_gt_i32 s0, 2
	s_cselect_b32 s0, s1, s0
	s_cmp_eq_u32 s0, 1
	s_cselect_b32 s1, s83, 0x600
	s_cmp_lg_u32 s0, 0
	s_cselect_b32 s14, s1, 0x300
	s_cmp_gt_i32 s63, 1
	s_cselect_b64 s[0:1], -1, 0
	s_cmp_ge_i32 s19, s14
	s_cselect_b64 s[14:15], -1, 0
	s_and_b64 s[16:17], s[14:15], exec
	s_cselect_b32 s19, s66, s19
	s_and_b64 s[0:1], s[14:15], s[0:1]
	s_cmp_lg_u64 s[14:15], 0
	s_addc_u32 s63, s63, 0
	s_mov_b32 s21, 1
	s_and_b64 vcc, exec, s[0:1]
	s_cbranch_vccnz .LBB0_474
	s_add_i32 s0, s63, s82
	s_add_i32 s1, s0, -3
	s_cmp_gt_i32 s0, 2
	s_cselect_b32 s0, s1, s0
	s_cmp_eq_u32 s0, 1
	s_cselect_b32 s1, 1, 2
	s_cmp_lg_u32 s0, 0
	s_cselect_b32 s0, s1, 0
	s_cmp_lt_i32 s0, 1
	s_cbranch_scc1 .LBB0_471
	s_cmp_lg_u32 s0, 1
	s_mov_b64 s[0:1], -1
	s_cbranch_scc0 .LBB0_468
	s_mul_hi_i32 s0, s19, 0x2aaaaaab
	s_lshr_b32 s1, s0, 31
	s_ashr_i32 s0, s0, 7
	s_add_i32 s0, s0, s1
	s_add_i32 s25, s0, 1
	s_mulk_i32 s0, 0x300
	s_sub_i32 s0, s19, s0
	s_mul_i32 s1, s0, 0x2aab
	s_lshr_b32 s12, s1, 31
	s_ashr_i32 s1, s1, 19
	s_add_i32 s1, s1, s12
	s_mul_i32 s12, s1, 48
	s_sub_i32 s0, s0, s12
	s_sext_i32_i16 s28, s0
	s_and_b32 s17, s28, 7
	s_mul_hi_i32 s0, s1, 0x1c00000
	s_mul_i32 s1, s1, 0x1c00000
	s_add_u32 s12, s96, s1
	s_addc_u32 s13, s97, s0
	s_lshl_b32 s0, s28, 4
	s_and_b32 s0, s0, 0xffffff80
	s_add_i32 s98, s0, 0xf00
	s_lshl_b64 s[0:1], s[98:99], 1
	s_add_u32 s20, s12, s0
	s_addc_u32 s21, s13, s1
	s_cmp_lg_u32 s25, 2
	s_mov_b64 s[0:1], -1
	s_cbranch_scc0 .LBB0_465
	s_cmp_eq_u32 s25, 0
	s_cselect_b64 s[0:1], -1, 0
	s_add_i32 s12, s19, 0x2ff
	s_lshr_b32 s13, s17, 1
	s_and_b32 s14, s28, 1
	s_cmpk_lt_u32 s12, 0x5ff
	s_mulk_i32 s13, 0x3800
	s_cselect_b32 s12, s13, 0
	s_cselect_b32 s13, s14, s17
	s_lshl_b32 s14, s13, 8
	s_and_b64 s[0:1], s[0:1], exec
	s_movk_i32 s0, 0x800
	s_cselect_b32 s15, s0, 0x200
	s_mov_b32 s0, 0xe000
	s_cselect_b32 s98, 0x3800, s0
	s_add_u32 s12, s20, s12
	s_addc_u32 s13, s21, 0
	s_mov_b64 s[0:1], 0
	s_mov_b32 s16, s98
	s_mov_b64 s[26:27], s[98:99]

.LBB0_499:
	s_bitcmp1_b32 s56, 0
	s_cselect_b64 s[0:1], -1, 0
	s_mov_b32 s24, 1
	s_and_b64 vcc, exec, s[0:1]
	s_cbranch_vccnz .LBB0_532
	s_cmp_eq_u32 s52, 3
	s_cbranch_scc0 .Lna_ld1_slow
	s_bitcmp1_b32 s60, 0
	s_cbranch_scc1 .Lna_ld1_single
	s_add_i32 s0, s60, 1
	s_cmp_eq_u32 s0, s70
	s_cbranch_scc1 .Lna_ld1_single
	s_ashr_i32 s0, s60, 1
	s_mul_hi_i32 s1, s0, 0xe0000
	s_mul_i32 s0, s0, 0xe0000
	s_add_u32 s0, s86, s0
	s_addc_u32 s1, s87, s1
	s_lshl_b32 s10, s57, 14
	s_add_i32 s10, s30, s10
	s_mov_b32 m0, s10
	s_nop 0
	global_load_lds_dwordx4 v182, s[0:1]
	s_add_i32 m0, s10, 0x400
	s_nop 0
	global_load_lds_dwordx4 v171, s[0:1]
	s_add_i32 s10, s57, 1
	s_cmp_lg_u32 s10, 6
	s_cselect_b32 s10, s10, 0
	s_add_u32 s0, s0, s98
	s_addc_u32 s1, s1, 0
	s_add_i32 s57, s10, 1
	s_cmp_lg_u32 s57, 6
	s_cselect_b32 s57, s57, 0
	s_lshl_b32 s10, s10, 14
	s_add_i32 s10, s30, s10
	s_mov_b32 m0, s10
	s_nop 0
	global_load_lds_dwordx4 v182, s[0:1]
	s_add_i32 m0, s10, 0x400
	s_nop 0
	global_load_lds_dwordx4 v171, s[0:1]
	s_add_i32 s60, s60, 2
	s_mov_b32 s24, 0
	s_mov_b32 s10, 0
	s_cmp_lg_u32 s60, s70
	s_cbranch_scc1 .LBB0_565
	s_branch .Lna_ld2_trans
.Lna_ld1_single:
	s_ashr_i32 s0, s60, 1
	s_mul_hi_i32 s1, s0, 0xe0000
	s_mul_i32 s0, s0, 0xe0000
	s_add_u32 s0, s86, s0
	s_addc_u32 s1, s87, s1
	s_bfe_i32 s10, s60, 0x10000
	s_and_b32 s10, s10, s98
	s_add_u32 s0, s0, s10
	s_addc_u32 s1, s1, 0
	s_lshl_b32 s10, s57, 14
	s_add_i32 s10, s30, s10
	s_mov_b32 m0, s10
	s_nop 0
	global_load_lds_dwordx4 v182, s[0:1]
	s_add_i32 m0, s10, 0x400
	s_nop 0
	global_load_lds_dwordx4 v171, s[0:1]
	s_add_i32 s0, s57, 1
	s_cmp_lg_u32 s0, 6
	s_cselect_b32 s57, s0, 0
	s_add_i32 s60, s60, 1
	s_cmp_lg_u32 s60, s70
	s_mov_b32 s24, 0
	s_cbranch_scc1 .LBB0_532
	s_branch .Lna_ld1_trans
